# v9 plus next-tile DMA issue pieces interleaved into the MFMA stream of the two projection K loops
# baseline (speedup 1.0000x reference)
.LBB0_130:
	v_add_u32_e32 v164, v168, v189
	v_add_u32_e32 v169, v146, v189
	s_waitcnt lgkmcnt(3)
	v_mfma_f32_32x32x16_bf16 v[0:15], v[128:131], v[132:135], v[0:15]
	ds_read_b128 v[156:159], v164
	s_add_i32 s47, s47, 1
	s_cbranch_vccnz .Lni_k0_0
	s_add_i32 s52, s48, 0x10000
	s_and_b32 s4, s52, 0x10000
	s_add_i32 s53, s4, s26
	s_add_i32 s54, s53, 0x8000
	s_add_u32 s82, s0, s81
	s_addk_i32 s82, 0x80
	s_and_b32 s82, s82, 0x7ff
	s_mov_b32 s83, 0
	s_add_u32 s4, s45, s82
	s_addc_u32 s5, s46, s83
	s_mov_b32 m0, s53
	global_load_lds_dwordx4 v145, s[4:5]
.Lni_k0_0:
	v_mfma_f32_32x32x16_bf16 v[16:31], v[152:155], v[132:135], v[16:31]
	ds_read_b128 v[132:135], v164 offset:4096
	s_cbranch_vccnz .Lni_k0_1
	s_add_u32 s4, s43, s82
	s_addc_u32 s5, s44, s83
	s_add_i32 s55, s53, 0x400
	s_mov_b32 m0, s55
	global_load_lds_dwordx4 v185, s[4:5]
.Lni_k0_1:
	s_waitcnt lgkmcnt(4)
	v_mfma_f32_32x32x16_bf16 v[32:47], v[128:131], v[136:139], v[32:47]
	ds_read_b128 v[160:163], v164 offset:8192
	s_cbranch_vccnz .Lni_k0_2
	s_add_u32 s4, s40, s82
	s_addc_u32 s5, s42, s83
	s_add_i32 s55, s53, 0x800
	s_mov_b32 m0, s55
	global_load_lds_dwordx4 v145, s[4:5]
.Lni_k0_2:
	v_mfma_f32_32x32x16_bf16 v[48:63], v[152:155], v[136:139], v[48:63]
	ds_read_b128 v[136:139], v164 offset:12288
	s_cbranch_vccnz .Lni_k0_3
	s_add_u32 s4, s37, s82
	s_addc_u32 s5, s39, s83
	s_add_i32 s55, s53, 0xc00
	s_mov_b32 m0, s55
	global_load_lds_dwordx4 v185, s[4:5]
.Lni_k0_3:
	s_waitcnt lgkmcnt(5)
	v_mfma_f32_32x32x16_bf16 v[64:79], v[128:131], v[140:143], v[64:79]
	ds_read_b128 v[164:167], v169 offset:32768
	s_cbranch_vccnz .Lni_k0_4
	s_add_u32 s4, s35, s82
	s_addc_u32 s5, s36, s83
	s_mov_b32 m0, s54
	global_load_lds_dwordx4 v145, s[4:5]
.Lni_k0_4:
	v_mfma_f32_32x32x16_bf16 v[80:95], v[152:155], v[140:143], v[80:95]
	ds_read_b128 v[140:143], v169 offset:36864
	v_add_u32_e32 v169, v168, v190
	s_cbranch_vccnz .Lni_k0_5
	s_add_u32 s4, s31, s82
	s_addc_u32 s5, s34, s83
	s_add_i32 s54, s53, 0x8400
	s_mov_b32 m0, s54
	global_load_lds_dwordx4 v185, s[4:5]
.Lni_k0_5:
	s_waitcnt lgkmcnt(6)
	v_mfma_f32_32x32x16_bf16 v[96:111], v[128:131], v[148:151], v[96:111]
	s_cbranch_vccnz .Lni_k0_6
	s_add_u32 s4, s29, s82
	s_addc_u32 s5, s30, s83
	s_add_i32 s54, s53, 0x8800
	s_mov_b32 m0, s54
	global_load_lds_dwordx4 v145, s[4:5]
.Lni_k0_6:
	v_mfma_f32_32x32x16_bf16 v[112:127], v[152:155], v[148:151], v[112:127]
	s_cbranch_vccnz .Lni_k0_7
	s_add_u32 s4, s27, s82
	s_addc_u32 s5, s28, s83
	s_add_i32 s53, s53, 0x8c00
	s_mov_b32 m0, s53
	global_load_lds_dwordx4 v185, s[4:5]
.Lni_k0_7:
	s_waitcnt lgkmcnt(1)
	v_mfma_f32_32x32x16_bf16 v[0:15], v[164:167], v[156:159], v[0:15]
	ds_read_b128 v[128:131], v169
	s_waitcnt lgkmcnt(1)
	v_mfma_f32_32x32x16_bf16 v[16:31], v[140:143], v[156:159], v[16:31]
	ds_read_b128 v[148:151], v169 offset:4096
	v_mfma_f32_32x32x16_bf16 v[32:47], v[164:167], v[132:135], v[32:47]
	ds_read_b128 v[152:155], v169 offset:8192
	v_mfma_f32_32x32x16_bf16 v[48:63], v[140:143], v[132:135], v[48:63]
	ds_read_b128 v[132:135], v169 offset:12288
	v_add_u32_e32 v169, v146, v190
	v_add_u32_e32 v146, v146, v191
	v_mfma_f32_32x32x16_bf16 v[64:79], v[164:167], v[160:163], v[64:79]
	ds_read_b128 v[156:159], v169 offset:32768
	v_mfma_f32_32x32x16_bf16 v[80:95], v[140:143], v[160:163], v[80:95]
	ds_read_b128 v[160:163], v169 offset:36864
	v_mfma_f32_32x32x16_bf16 v[96:111], v[164:167], v[136:139], v[96:111]
	v_add_u32_e32 v164, v168, v191
	v_mfma_f32_32x32x16_bf16 v[112:127], v[140:143], v[136:139], v[112:127]
	s_waitcnt lgkmcnt(1)
	v_mfma_f32_32x32x16_bf16 v[0:15], v[156:159], v[128:131], v[0:15]
	ds_read_b128 v[136:139], v164
	s_waitcnt lgkmcnt(1)
	v_mfma_f32_32x32x16_bf16 v[16:31], v[160:163], v[128:131], v[16:31]
	ds_read_b128 v[128:131], v164 offset:4096
	v_mfma_f32_32x32x16_bf16 v[32:47], v[156:159], v[148:151], v[32:47]
	ds_read_b128 v[140:143], v164 offset:8192
	v_mfma_f32_32x32x16_bf16 v[48:63], v[160:163], v[148:151], v[48:63]
	ds_read_b128 v[148:151], v164 offset:12288
	v_mfma_f32_32x32x16_bf16 v[64:79], v[156:159], v[152:155], v[64:79]
	ds_read_b128 v[164:167], v146 offset:32768
	v_mfma_f32_32x32x16_bf16 v[80:95], v[160:163], v[152:155], v[80:95]
	ds_read_b128 v[152:155], v146 offset:36864
	v_mfma_f32_32x32x16_bf16 v[96:111], v[156:159], v[132:135], v[96:111]
	v_mfma_f32_32x32x16_bf16 v[112:127], v[160:163], v[132:135], v[112:127]
	s_waitcnt lgkmcnt(1)
	v_mfma_f32_32x32x16_bf16 v[0:15], v[164:167], v[136:139], v[0:15]
	s_waitcnt lgkmcnt(0)
	v_mfma_f32_32x32x16_bf16 v[16:31], v[152:155], v[136:139], v[16:31]
	v_mfma_f32_32x32x16_bf16 v[32:47], v[164:167], v[128:131], v[32:47]
	v_mfma_f32_32x32x16_bf16 v[48:63], v[152:155], v[128:131], v[48:63]
	v_mfma_f32_32x32x16_bf16 v[64:79], v[164:167], v[140:143], v[64:79]
	v_mfma_f32_32x32x16_bf16 v[80:95], v[152:155], v[140:143], v[80:95]
	v_mfma_f32_32x32x16_bf16 v[96:111], v[164:167], v[148:151], v[96:111]
	v_mfma_f32_32x32x16_bf16 v[112:127], v[152:155], v[148:151], v[112:127]
	s_add_u32 s0, s0, 0x80
	s_addc_u32 s1, s1, 0
	s_mov_b32 s48, s52
	s_cmpk_lg_i32 s0, 0x800
	s_cbranch_scc0 .LBB0_135

.LBB0_133:
	s_andn2_b64 vcc, exec, s[4:5]
	s_branch .LBB0_130

.LBB0_725:
	v_add_u32_e32 v162, v166, v189
	v_add_u32_e32 v167, v144, v189
	s_waitcnt lgkmcnt(3)
	v_mfma_f32_32x32x16_bf16 v[0:15], v[128:131], v[132:135], v[0:15]
	ds_read_b128 v[154:157], v162
	s_add_i32 s45, s45, 1
	s_cbranch_vccnz .Lni_k1_0
	s_add_i32 s50, s46, 0x10000
	s_and_b32 s6, s50, 0x10000
	s_add_i32 s51, s6, s26
	s_add_i32 s52, s51, 0x8000
	s_add_u32 s82, s4, s81
	s_addk_i32 s82, 0x80
	s_and_b32 s82, s82, 0x7ff
	s_mov_b32 s83, 0
	s_add_u32 s6, s43, s82
	s_addc_u32 s7, s44, s83
	s_mov_b32 m0, s51
	global_load_lds_dwordx4 v177, s[6:7]
.Lni_k1_0:
	v_mfma_f32_32x32x16_bf16 v[16:31], v[150:153], v[132:135], v[16:31]
	ds_read_b128 v[132:135], v162 offset:4096
	s_cbranch_vccnz .Lni_k1_1
	s_add_u32 s6, s41, s82
	s_addc_u32 s7, s42, s83
	s_add_i32 s53, s51, 0x400
	s_mov_b32 m0, s53
	global_load_lds_dwordx4 v185, s[6:7]
.Lni_k1_1:
	s_waitcnt lgkmcnt(4)
	v_mfma_f32_32x32x16_bf16 v[32:47], v[128:131], v[136:139], v[32:47]
	ds_read_b128 v[158:161], v162 offset:8192
	s_cbranch_vccnz .Lni_k1_2
	s_add_u32 s6, s39, s82
	s_addc_u32 s7, s40, s83
	s_add_i32 s53, s51, 0x800
	s_mov_b32 m0, s53
	global_load_lds_dwordx4 v177, s[6:7]
.Lni_k1_2:
	v_mfma_f32_32x32x16_bf16 v[48:63], v[150:153], v[136:139], v[48:63]
	ds_read_b128 v[136:139], v162 offset:12288
	s_cbranch_vccnz .Lni_k1_3
	s_add_u32 s6, s37, s82
	s_addc_u32 s7, s38, s83
	s_add_i32 s53, s51, 0xc00
	s_mov_b32 m0, s53
	global_load_lds_dwordx4 v185, s[6:7]
.Lni_k1_3:
	s_waitcnt lgkmcnt(5)
	v_mfma_f32_32x32x16_bf16 v[64:79], v[128:131], v[140:143], v[64:79]
	ds_read_b128 v[162:165], v167 offset:32768
	s_cbranch_vccnz .Lni_k1_4
	s_add_u32 s6, s35, s82
	s_addc_u32 s7, s36, s83
	s_mov_b32 m0, s52
	global_load_lds_dwordx4 v177, s[6:7]
.Lni_k1_4:
	v_mfma_f32_32x32x16_bf16 v[80:95], v[150:153], v[140:143], v[80:95]
	ds_read_b128 v[140:143], v167 offset:36864
	v_add_u32_e32 v167, v166, v190
	s_cbranch_vccnz .Lni_k1_5
	s_add_u32 s6, s31, s82
	s_addc_u32 s7, s34, s83
	s_add_i32 s52, s51, 0x8400
	s_mov_b32 m0, s52
	global_load_lds_dwordx4 v185, s[6:7]
.Lni_k1_5:
	s_waitcnt lgkmcnt(6)
	v_mfma_f32_32x32x16_bf16 v[96:111], v[128:131], v[146:149], v[96:111]
	s_cbranch_vccnz .Lni_k1_6
	s_add_u32 s6, s29, s82
	s_addc_u32 s7, s30, s83
	s_add_i32 s52, s51, 0x8800
	s_mov_b32 m0, s52
	global_load_lds_dwordx4 v177, s[6:7]
.Lni_k1_6:
	v_mfma_f32_32x32x16_bf16 v[112:127], v[150:153], v[146:149], v[112:127]
	s_cbranch_vccnz .Lni_k1_7
	s_add_u32 s6, s27, s82
	s_addc_u32 s7, s28, s83
	s_add_i32 s51, s51, 0x8c00
	s_mov_b32 m0, s51
	global_load_lds_dwordx4 v185, s[6:7]
.Lni_k1_7:
	s_waitcnt lgkmcnt(1)
	v_mfma_f32_32x32x16_bf16 v[0:15], v[162:165], v[154:157], v[0:15]
	ds_read_b128 v[128:131], v167
	s_waitcnt lgkmcnt(1)
	v_mfma_f32_32x32x16_bf16 v[16:31], v[140:143], v[154:157], v[16:31]
	ds_read_b128 v[146:149], v167 offset:4096
	v_mfma_f32_32x32x16_bf16 v[32:47], v[162:165], v[132:135], v[32:47]
	ds_read_b128 v[150:153], v167 offset:8192
	v_mfma_f32_32x32x16_bf16 v[48:63], v[140:143], v[132:135], v[48:63]
	ds_read_b128 v[132:135], v167 offset:12288
	v_add_u32_e32 v167, v144, v190
	v_add_u32_e32 v144, v144, v191
	v_mfma_f32_32x32x16_bf16 v[64:79], v[162:165], v[158:161], v[64:79]
	ds_read_b128 v[154:157], v167 offset:32768
	v_mfma_f32_32x32x16_bf16 v[80:95], v[140:143], v[158:161], v[80:95]
	ds_read_b128 v[158:161], v167 offset:36864
	v_mfma_f32_32x32x16_bf16 v[96:111], v[162:165], v[136:139], v[96:111]
	v_add_u32_e32 v162, v166, v191
	v_mfma_f32_32x32x16_bf16 v[112:127], v[140:143], v[136:139], v[112:127]
	s_waitcnt lgkmcnt(1)
	v_mfma_f32_32x32x16_bf16 v[0:15], v[154:157], v[128:131], v[0:15]
	ds_read_b128 v[136:139], v162
	s_waitcnt lgkmcnt(1)
	v_mfma_f32_32x32x16_bf16 v[16:31], v[158:161], v[128:131], v[16:31]
	ds_read_b128 v[128:131], v162 offset:4096
	v_mfma_f32_32x32x16_bf16 v[32:47], v[154:157], v[146:149], v[32:47]
	ds_read_b128 v[140:143], v162 offset:8192
	v_mfma_f32_32x32x16_bf16 v[48:63], v[158:161], v[146:149], v[48:63]
	ds_read_b128 v[146:149], v162 offset:12288
	v_mfma_f32_32x32x16_bf16 v[64:79], v[154:157], v[150:153], v[64:79]
	ds_read_b128 v[162:165], v144 offset:32768
	v_mfma_f32_32x32x16_bf16 v[80:95], v[158:161], v[150:153], v[80:95]
	ds_read_b128 v[150:153], v144 offset:36864
	v_mfma_f32_32x32x16_bf16 v[96:111], v[154:157], v[132:135], v[96:111]
	v_mfma_f32_32x32x16_bf16 v[112:127], v[158:161], v[132:135], v[112:127]
	s_waitcnt lgkmcnt(1)
	v_mfma_f32_32x32x16_bf16 v[0:15], v[162:165], v[136:139], v[0:15]
	s_waitcnt lgkmcnt(0)
	v_mfma_f32_32x32x16_bf16 v[16:31], v[150:153], v[136:139], v[16:31]
	v_mfma_f32_32x32x16_bf16 v[32:47], v[162:165], v[128:131], v[32:47]
	v_mfma_f32_32x32x16_bf16 v[48:63], v[150:153], v[128:131], v[48:63]
	v_mfma_f32_32x32x16_bf16 v[64:79], v[162:165], v[140:143], v[64:79]
	v_mfma_f32_32x32x16_bf16 v[80:95], v[150:153], v[140:143], v[80:95]
	v_mfma_f32_32x32x16_bf16 v[96:111], v[162:165], v[146:149], v[96:111]
	v_mfma_f32_32x32x16_bf16 v[112:127], v[150:153], v[146:149], v[112:127]
	s_add_u32 s4, s4, 0x80
	s_addc_u32 s5, s5, 0
	s_mov_b32 s46, s50
	s_cmpk_lg_i32 s4, 0x800
	s_cbranch_scc0 .LBB0_730

.LBB0_728:
	s_andn2_b64 vcc, exec, s[6:7]
	s_branch .LBB0_725
